# up-projection epilogue: five VALU results that are overwritten before anyone reads them (address arithmetic left behind by the LDS staging of the epilogue inputs) removed
# baseline (speedup 1.0000x reference)
;     __device__ __forceinline__ void operator()(const f32x4 (&acc)[2][2][4][2], const Unit& u, int wr, int wc, int fr, int fq) const {
;     ...
;         const int lane = otid() & 63;
;         const int src1 = (lane & 48) | ((fr + 15) & 15), src2 = (lane & 48) | ((fr + 14) & 15);
;         float rs[2][4];
; #pragma unroll
;         for (int ai = 0; ai < 2; ++ai)
; #pragma unroll
;             for (int m = 0; m < 4; ++m) rs[ai][m] = __builtin_amdgcn_rsqf((float)ss[u.pm * BM + ai * HALF + wr * 64 + m * 16 + fr] * (1.f / (2048.f * 262144.f)) + 1e-6f);
; #pragma unroll
;         for (int n = 0; n < 2; ++n) {
;             const int cbase = 128 * u.pn + 32 * wc + 16 * n + 4 * fq;
;             const f32x4 w0 = *(const f32x4*)(cw + cbase), w1 = *(const f32x4*)(cw + FF + cbase), w2 = *(const f32x4*)(cw + 2 * FF + cbase), b4 = *(const f32x4*)(cb + cbase);
; #pragma unroll
;             for (int ai = 0; ai < 2; ++ai) {
;                 const int slab = u.pm * 4 + 2 * ai + wr;
;                 f32x4 r1p = (f32x4){0.f, 0.f, 0.f, 0.f}, r2p = (f32x4){0.f, 0.f, 0.f, 0.f};
; #pragma unroll
;                 for (int m = 0; m < 4; ++m) {
;                     const f32x4 g = acc[ai][1][m][n] * rs[ai][m], v = acc[ai][0][m][n] * rs[ai][m];
;                     f32x4 r1, r2, a;
; #pragma unroll
;                     for (int e = 0; e < 4; ++e) { r1[e] = __shfl(g[e], src1); r2[e] = __shfl(g[e], src2); }
; #pragma unroll
;                     for (int e = 0; e < 4; ++e) {
;                         const float p1 = fr >= 1 ? r1[e] : r1p[e], p2 = fr >= 2 ? r2[e] : r2p[e];
;                         const float gg = b4[e] + w0[e] * p2 + w1[e] * p1 + w2[e] * g[e];
;                         a[e] = gg * __builtin_amdgcn_rcpf(1.f + __expf(-gg)) * v[e];
;                     }
;                     r1p = r1; r2p = r2;
;                     const size_t row = (size_t)(u.pm * BM + ai * HALF + wr * 64 + m * 16 + fr);
;                     if (m == 0 && fr < 2) {
;                         *(f32x4*)(GF + (size_t)(slab * 2 + fr) * FF + cbase) = g; *(f32x4*)(VF + (size_t)(slab * 2 + fr) * FF + cbase) = v;
;                     } else {
;                         typedef unsigned u32x2v __attribute__((ext_vector_type(2)));
;                         u32x2v w; w.x = cvt_pk_bf16(a[0], a[1]); w.y = cvt_pk_bf16(a[2], a[3]);
;                         *(u32x2v*)(ACT + row * FF + cbase) = w;
.LBB0_41:
	v_lshl_add_u32 v160, s66, 8, v193
	v_mov_b32_e32 v148, v227
	v_bfe_u32 v205, v227, 4, 1
	v_mul_u32_u24_e32 v205, 24, v205
	s_and_b32 s98, s65, 1
	s_lshl_b32 s98, s98, 12
	s_add_i32 s98, s98, 0x20000
	s_add_i32 s99, s98, 0x800
	v_lshl_add_u32 v114, v193, 3, s98
	ds_read_b64 v[146:147], v114
	v_lshl_or_b32 v156, s64, 7, v198
	v_ashrrev_i32_e32 v157, 31, v156
	ds_read_b64 v[190:191], v114 offset:128
	ds_read_b64 v[188:189], v114 offset:256
	ds_read_b64 v[186:187], v114 offset:384
	ds_read_b64 v[176:177], v114 offset:1024
	ds_read_b64 v[174:175], v114 offset:1152
	ds_read_b64 v[172:173], v114 offset:1280
	ds_read_b64 v[170:171], v114 offset:1408
	v_lshlrev_b64 v[158:159], 2, v[156:157]
	v_lshl_add_u32 v166, v198, 2, s99
	v_lshl_add_u64 v[164:165], s[54:55], 0, v[158:159]
	ds_read_b128 v[114:117], v166
	ds_read_b128 v[138:141], v166 offset:512
	ds_read_b128 v[130:133], v166 offset:1024
	s_nop 0
	ds_read_b128 v[118:121], v166 offset:1536
	s_waitcnt lgkmcnt(0)
	v_ffbh_u32_e32 v149, v147
	v_min_u32_e32 v149, 32, v149
	v_lshlrev_b64 v[146:147], v149, v[146:147]
	v_min_u32_e32 v146, 1, v146
	v_or_b32_e32 v146, v147, v146
	v_cvt_f32_u32_e32 v146, v146
	v_sub_u32_e32 v149, 32, v149
	v_and_b32_e32 v147, 48, v148
	v_or3_b32 v148, v147, v195, v236
	v_ldexp_f32 v146, v146, v149
	v_fmamk_f32 v146, v146, 0x31000000, v232
	v_rsq_f32_e32 v162, v146
	v_or3_b32 v146, v147, v196, v236
	v_lshlrev_b32_e32 v200, 2, v146
	v_lshlrev_b32_e32 v161, 2, v148
	v_pk_mul_f32 v[146:147], v[134:135], v[162:163] op_sel_hi:[1,0]
	v_pk_mul_f32 v[148:149], v[136:137], v[162:163] op_sel_hi:[1,0]
	s_nop 1
	v_mov_b32_dpp v163, v146 row_ror:2 row_mask:0xf bank_mask:0xf
	v_mov_b32_dpp v179, v146 row_ror:1 row_mask:0xf bank_mask:0xf
	v_mov_b32_dpp v181, v147 row_ror:1 row_mask:0xf bank_mask:0xf
	v_mov_b32_dpp v201, v147 row_ror:2 row_mask:0xf bank_mask:0xf
	v_mov_b32_dpp v183, v148 row_ror:1 row_mask:0xf bank_mask:0xf
	v_mov_b32_dpp v202, v148 row_ror:2 row_mask:0xf bank_mask:0xf
	v_mov_b32_dpp v185, v149 row_ror:1 row_mask:0xf bank_mask:0xf
	v_mov_b32_dpp v203, v149 row_ror:2 row_mask:0xf bank_mask:0xf
	s_waitcnt lgkmcnt(7)
	v_pk_mul_f32 v[136:137], v[144:145], v[162:163] op_sel_hi:[1,0]
	v_pk_mul_f32 v[134:135], v[142:143], v[162:163] op_sel_hi:[1,0]
	s_and_saveexec_b64 s[10:11], s[42:43]
	s_xor_b64 s[10:11], exec, s[10:11]
	s_movk_i32 s17, 0x2b00
	s_movk_i32 s84, 0x300
	s_mov_b32 s86, 0x24000
	s_mov_b32 s88, 0x48800000
	s_cbranch_execz .LBB0_43
	v_mov_b32_e32 v184, v133
	s_waitcnt lgkmcnt(1)
	s_waitcnt lgkmcnt(0)
	v_fma_f32 v144, v117, v203, v121
	v_fma_f32 v143, v141, v185, v144
	v_fma_f32 v142, v149, v184, v143
	v_mul_f32_e32 v143, 0xbfb8aa3b, v142
	v_exp_f32_e32 v143, v143
	v_mov_b32_e32 v149, v140
	v_mov_b32_e32 v182, v132
	v_mov_b32_e32 v180, v131
	v_add_f32_e32 v143, 1.0, v143
	v_rcp_f32_e32 v143, v143
	v_mov_b32_e32 v178, v130
	v_mul_f32_e32 v142, v142, v143
	v_mul_f32_e32 v144, v137, v142
	v_fma_f32 v137, v116, v202, v120
	v_fma_f32 v137, v149, v183, v137
	v_fma_f32 v137, v148, v182, v137
	v_mul_f32_e32 v142, 0xbfb8aa3b, v137
	v_exp_f32_e32 v142, v142
	v_fma_f32 v143, v115, v201, v119
	v_add_f32_e32 v142, 1.0, v142
	v_rcp_f32_e32 v142, v142
	s_nop 0
	v_mul_f32_e32 v137, v137, v142
	v_mul_f32_e32 v142, v136, v137
	v_mov_b32_e32 v136, v147
	v_mov_b32_e32 v147, v138
	v_fma_f32 v137, v139, v181, v143
	v_fma_f32 v136, v136, v180, v137
	v_mul_f32_e32 v137, 0xbfb8aa3b, v136
	v_exp_f32_e32 v137, v137
	v_fma_f32 v143, v114, v163, v118
	v_add_f32_e32 v137, 1.0, v137
	v_rcp_f32_e32 v137, v137
	s_nop 0
	v_mul_f32_e32 v136, v136, v137
	v_mul_f32_e32 v135, v135, v136
	s_nop 0
	v_fma_f32 v137, v147, v179, v143
	v_fma_f32 v136, v146, v178, v137
	v_mul_f32_e32 v137, 0xbfb8aa3b, v136
	v_exp_f32_e32 v137, v137
	s_nop 0
	v_add_f32_e32 v137, 1.0, v137
	v_rcp_f32_e32 v137, v137
	s_nop 0
	v_mul_f32_e32 v136, v136, v137
	v_mul_f32_e32 v134, v134, v136
	v_mov_b64_e32 v[136:137], s[48:49]
	v_mad_i64_i32 v[136:137], s[12:13], v160, s17, v[136:137]
	v_cvt_pk_bf16_f32 v134, v134, v135
	v_cvt_pk_bf16_f32 v135, v142, v144
	v_lshl_add_u64 v[136:137], v[156:157], 1, v[136:137]
	v_mov_b32_e32 v220, v134
	v_mov_b32_e32 v221, v135

;     __device__ __forceinline__ void operator()(const f32x4 (&acc)[2][2][4][2], const Unit& u, int wr, int wc, int fr, int fq) const {
;     ...
;             for (int m = 0; m < 4; ++m) rs[ai][m] = __builtin_amdgcn_rsqf((float)ss[u.pm * BM + ai * HALF + wr * 64 + m * 16 + fr] * (1.f / (2048.f * 262144.f)) + 1e-6f);
; #pragma unroll
;         for (int n = 0; n < 2; ++n) {
;             const int cbase = 128 * u.pn + 32 * wc + 16 * n + 4 * fq;
;             const f32x4 w0 = *(const f32x4*)(cw + cbase), w1 = *(const f32x4*)(cw + FF + cbase), w2 = *(const f32x4*)(cw + 2 * FF + cbase), b4 = *(const f32x4*)(cb + cbase);
; #pragma unroll
;             for (int ai = 0; ai < 2; ++ai) {
;                 const int slab = u.pm * 4 + 2 * ai + wr;
;                 f32x4 r1p = (f32x4){0.f, 0.f, 0.f, 0.f}, r2p = (f32x4){0.f, 0.f, 0.f, 0.f};
; #pragma unroll
;                 for (int m = 0; m < 4; ++m) {
;                     const f32x4 g = acc[ai][1][m][n] * rs[ai][m], v = acc[ai][0][m][n] * rs[ai][m];
;                     f32x4 r1, r2, a;
; #pragma unroll
;                     for (int e = 0; e < 4; ++e) { r1[e] = __shfl(g[e], src1); r2[e] = __shfl(g[e], src2); }
; #pragma unroll
;                     for (int e = 0; e < 4; ++e) {
;                         const float p1 = fr >= 1 ? r1[e] : r1p[e], p2 = fr >= 2 ? r2[e] : r2p[e];
;                         const float gg = b4[e] + w0[e] * p2 + w1[e] * p1 + w2[e] * g[e];
;                         a[e] = gg * __builtin_amdgcn_rcpf(1.f + __expf(-gg)) * v[e];
;                     }
;                     r1p = r1; r2p = r2;
;                     const size_t row = (size_t)(u.pm * BM + ai * HALF + wr * 64 + m * 16 + fr);
;                     if (m == 0 && fr < 2) {
;                         *(f32x4*)(GF + (size_t)(slab * 2 + fr) * FF + cbase) = g; *(f32x4*)(VF + (size_t)(slab * 2 + fr) * FF + cbase) = v;
;                     } else {
;                         typedef unsigned u32x2v __attribute__((ext_vector_type(2)));
;                         u32x2v w; w.x = cvt_pk_bf16(a[0], a[1]); w.y = cvt_pk_bf16(a[2], a[3]);
;                         *(u32x2v*)(ACT + row * FF + cbase) = w;
;                     }
;                     if (m == 3 && fr >= 14) *(f32x4*)(GL + (size_t)(slab * 2 + fr - 14) * FF + cbase) = g;
.LBB0_53:
	s_or_b64 exec, exec, s[10:11]
	s_nop 0
	v_or_b32_e32 v70, 16, v156
	v_ashrrev_i32_e32 v71, 31, v70
	v_lshlrev_b64 v[70:71], 2, v[70:71]
	ds_read_b128 v[66:69], v166 offset:64
	ds_read_b128 v[78:81], v166 offset:576
	ds_read_b128 v[74:77], v166 offset:1088
	s_nop 0
	ds_read_b128 v[70:73], v166 offset:1600
	v_mov_b32_e32 v163, v162
	v_mov_b32_e32 v120, v162
	v_mov_b32_e32 v121, v162
	v_pk_mul_f32 v[84:85], v[60:61], v[120:121]
	v_pk_mul_f32 v[82:83], v[58:59], v[162:163]
	s_nop 1
	v_mov_b32_dpp v101, v82 row_ror:1 row_mask:0xf bank_mask:0xf
	v_mov_b32_dpp v91, v82 row_ror:2 row_mask:0xf bank_mask:0xf
	v_mov_b32_dpp v115, v83 row_ror:1 row_mask:0xf bank_mask:0xf
	v_mov_b32_dpp v93, v83 row_ror:2 row_mask:0xf bank_mask:0xf
	v_mov_b32_dpp v117, v84 row_ror:1 row_mask:0xf bank_mask:0xf
	v_mov_b32_dpp v95, v84 row_ror:2 row_mask:0xf bank_mask:0xf
	v_mov_b32_dpp v119, v85 row_ror:1 row_mask:0xf bank_mask:0xf
	v_mov_b32_dpp v103, v85 row_ror:2 row_mask:0xf bank_mask:0xf
	v_pk_mul_f32 v[60:61], v[64:65], v[120:121]
	v_pk_mul_f32 v[58:59], v[62:63], v[162:163]
	s_and_saveexec_b64 s[10:11], s[42:43]
	s_xor_b64 s[10:11], exec, s[10:11]
	s_cbranch_execz .LBB0_55
	s_waitcnt lgkmcnt(0)
	s_waitcnt lgkmcnt(0)
	v_mov_b32_e32 v118, v77
	s_waitcnt lgkmcnt(1)
	s_waitcnt lgkmcnt(0)
	v_fma_f32 v64, v69, v103, v73
	v_fma_f32 v63, v81, v119, v64
	v_fma_f32 v62, v85, v118, v63
	v_mul_f32_e32 v63, 0xbfb8aa3b, v62
	v_exp_f32_e32 v63, v63
	v_mov_b32_e32 v85, v80
	v_mov_b32_e32 v116, v76
	v_mov_b32_e32 v114, v75
	v_add_f32_e32 v63, 1.0, v63
	v_rcp_f32_e32 v63, v63
	v_mov_b32_e32 v100, v74
	v_mul_f32_e32 v62, v62, v63
	v_mul_f32_e32 v64, v61, v62
	v_fma_f32 v61, v68, v95, v72
	v_fma_f32 v61, v85, v117, v61
	v_fma_f32 v61, v84, v116, v61
	v_mul_f32_e32 v62, 0xbfb8aa3b, v61
	v_exp_f32_e32 v62, v62
	v_fma_f32 v63, v67, v93, v71
	v_add_f32_e32 v62, 1.0, v62
	v_rcp_f32_e32 v62, v62
	s_nop 0
	v_mul_f32_e32 v61, v61, v62
	v_mul_f32_e32 v62, v60, v61
	v_mov_b32_e32 v60, v83
	v_mov_b32_e32 v83, v78
	v_fma_f32 v61, v79, v115, v63
	v_fma_f32 v60, v60, v114, v61
	v_mul_f32_e32 v61, 0xbfb8aa3b, v60
	v_exp_f32_e32 v61, v61
	v_fma_f32 v63, v66, v91, v70
	v_add_f32_e32 v61, 1.0, v61
	v_rcp_f32_e32 v61, v61
	s_nop 0
	v_mul_f32_e32 v60, v60, v61
	v_mul_f32_e32 v59, v59, v60
	s_nop 0
	v_fma_f32 v61, v83, v101, v63
	v_fma_f32 v60, v82, v100, v61
	v_mul_f32_e32 v61, 0xbfb8aa3b, v60
	v_exp_f32_e32 v61, v61
	s_nop 0
	v_add_f32_e32 v61, 1.0, v61
	v_rcp_f32_e32 v61, v61
	s_nop 0
	v_mul_f32_e32 v60, v60, v61
	v_mul_f32_e32 v58, v58, v60
	v_mov_b64_e32 v[60:61], s[48:49]
	v_mad_i64_i32 v[60:61], s[12:13], v160, s17, v[60:61]
	v_cvt_pk_bf16_f32 v58, v58, v59
	v_cvt_pk_bf16_f32 v59, v62, v64
	v_lshl_add_u64 v[60:61], v[156:157], 1, v[60:61]
	v_mov_b32_e32 v64, v77
	v_mov_b32_e32 v62, v75
	s_nop 1
	v_permlane16_swap_b32_e32 v220, v58
	v_permlane16_swap_b32_e32 v221, v59
	v_mov_b32_e32 v222, v58
	v_mov_b32_e32 v223, v59
	v_add_co_u32_e64 v60, s[98:99], v60, v205
	s_nop 1
	v_addc_co_u32_e64 v61, s[98:99], 0, v61, s[98:99]
	global_store_dwordx4 v[60:61], v[220:223], off nt
